# SwiGLU epilogue: all stores after a drain at the end; first two DMA waits of the next tile relaxed
# baseline (speedup 1.0000x reference)
; #define PG8_STAGE(bufoff, gbase, voff) do { _Pragma("unroll") for (int _i = 0; _i < 2; ++_i) { \
;         const unsigned _m0 = ldsb + (unsigned)((bufoff) + _i * 8192); const char* _gb = (const char*)(gbase); \
;         asm volatile("s_mov_b32 m0, %0\n\ts_nop 0\n\tglobal_load_lds_dwordx4 %1, %2" :: "s"(_m0), "v"((voff)[_i]), "s"(_gb) : "m0", "memory"); } } while (0)
; #define PG8_LDA(dst, b, h) do { _Pragma("unroll") for (int m = 0; m < 4; ++m) _Pragma("unroll") for (int k = 0; k < 2; ++k) dst[m][k] = *(const LAS bf16x8*)(lds + PG8_SA(b, h) + aoff + m * 2048 + k * 1024); } while (0)
; #define PG8_LDB(dst, b, h) do { _Pragma("unroll") for (int n = 0; n < 2; ++n) _Pragma("unroll") for (int k = 0; k < 2; ++k) dst[n][k] = *(const LAS bf16x8*)(lds + PG8_SB(b, h) + boff + n * 2048 + k * 1024); } while (0)
; #define PG8_MMA(ai, bj, At, Bt) do { __builtin_amdgcn_s_setprio(1); _Pragma("unroll") for (int m = 0; m < 4; ++m) _Pragma("unroll") for (int n = 0; n < 2; ++n) _Pragma("unroll") for (int k = 0; k < 2; ++k) \
;         acc[ai][bj][m][n] = __builtin_amdgcn_mfma_f32_16x16x32_bf16(Bt[n][k], At[m][k], acc[ai][bj][m][n], 0, 0, 0); __builtin_amdgcn_s_setprio(0); } while (0)
; #define PG8_WAIT_V(n) asm volatile("s_waitcnt vmcnt(" #n ")" ::: "memory")
; #define PG8_WAIT_L(n) asm volatile("s_waitcnt lgkmcnt(" #n ")" ::: "memory")
; template <class Epi, bool ALIGN_EPI>
; __device__ __forceinline__ void gemm_phase(LAS unsigned char* lds, const Gemm g, const StaticOrder& S, const Epi& E) {
;     ...
;         for (int t = 0; t < nt; t += 2) {
;             const bool last = (t == nt - 2);
;             const char* a1 = cA + (size_t)(t + 1) * kstep;
;             const char* a2 = last ? nA : cA + (size_t)(t + 2) * kstep; const char* b2 = last ? nB : cB + (size_t)(t + 2) * kstep;
;             const char* a3 = a2 + kstep; const char* b3 = b2 + kstep;
;             PG8_LDB(B0, 0, 0); PG8_LDB(B1, 0, 1); PG8_SCHED; PG8_LDA(At, 0, 0); PG8_STAGE(PG8_SA(1, 1), a1 + hstepA, voffA);
;             PG8_WAIT_V(8); PG8_WAIT_L(0); PG8_BAR; PG8_MMA(0, 0, At, B0); PG8_MMA(0, 1, At, B1); PG8_BAR; PG8_SCHED;
;             PG8_LDA(At, 0, 1); PG8_STAGE(PG8_SB(0, 0), b2, voffB); PG8_STAGE(PG8_SB(0, 1), b2 + hstepB, voffB); PG8_STAGE(PG8_SA(0, 0), a2, voffA);
;             PG8_WAIT_V(8); PG8_WAIT_L(0); PG8_BAR; PG8_MMA(1, 0, At, B0); PG8_MMA(1, 1, At, B1); PG8_BAR; PG8_SCHED;
.LBB0_305:
	s_ashr_i32 s37, s36, 31
	s_lshl_b64 s[4:5], s[36:37], 19
	s_add_u32 s38, s18, s4
	s_addc_u32 s39, s19, s5
	s_and_b64 s[4:5], s[8:9], exec
	s_cselect_b32 s4, s39, s59
	s_cselect_b32 s5, s38, s58
	s_ashr_i32 s35, s34, 31
	s_lshl_b64 s[50:51], s[34:35], 19
	s_add_u32 s90, s1, s50
	s_addc_u32 s91, s14, s51
	s_and_b64 s[50:51], s[8:9], exec
	s_cselect_b32 s35, s91, s57
	s_cselect_b32 s37, s90, s56
	s_add_u32 s41, s56, 0x100
	s_addc_u32 s49, s57, 0
	s_add_u32 s92, s58, 0x40080
	s_addc_u32 s93, s59, 0
	s_mov_b32 s50, -2
	v_add_u32_e32 v134, 0x10000, v185
	v_add_u32_e32 v158, 0x14000, v185
	ds_read_b128 v[74:77], v134
	ds_read_b128 v[94:97], v134 offset:1024
	ds_read_b128 v[114:117], v134 offset:2048
	ds_read_b128 v[134:137], v134 offset:3072
	ds_read_b128 v[146:149], v158
	ds_read_b128 v[150:153], v158 offset:1024
	ds_read_b128 v[154:157], v158 offset:2048
	ds_read_b128 v[158:161], v158 offset:3072
	s_add_u32 s30, s92, 0xfffc0080
	s_addc_u32 s31, s93, -1
	s_cmp_eq_u32 s50, 12
	s_cselect_b32 s60, s5, s30
	s_cselect_b32 s61, s4, s31
	s_cselect_b32 s58, s37, s41
	s_cselect_b32 s59, s35, s49
	s_add_u32 s56, s60, 0x80
	s_addc_u32 s57, s61, 0
	ds_read_b128 v[162:165], v186
	ds_read_b128 v[166:169], v186 offset:1024
	ds_read_b128 v[170:173], v186 offset:2048
	ds_read_b128 v[174:177], v186 offset:3072
	ds_read_b128 v[188:191], v186 offset:4096
	ds_read_b128 v[202:205], v186 offset:5120
	ds_read_b128 v[206:209], v186 offset:6144
	ds_read_b128 v[210:213], v186 offset:7168
	s_mov_b32 m0, s67
	s_nop 0
	global_load_lds_dwordx4 v0, s[92:93]
	s_nop 0
	s_mov_b32 m0, s65
	s_nop 0
	global_load_lds_dwordx4 v181, s[92:93]
	s_waitcnt lgkmcnt(0)
	s_barrier
	s_setprio 1
	s_waitcnt lgkmcnt(0)
	v_mfma_f32_16x16x32_bf16 v[142:145], v[74:77], v[162:165], 0
	v_mfma_f32_16x16x32_bf16 v[142:145], v[94:97], v[166:169], v[142:145]
	v_mfma_f32_16x16x32_bf16 v[138:141], v[114:117], v[162:165], 0
	v_mfma_f32_16x16x32_bf16 v[138:141], v[134:137], v[166:169], v[138:141]
	v_mfma_f32_16x16x32_bf16 v[130:133], v[146:149], v[162:165], 0
	v_mfma_f32_16x16x32_bf16 v[130:133], v[150:153], v[166:169], v[130:133]
	v_mfma_f32_16x16x32_bf16 v[126:129], v[154:157], v[162:165], 0
	v_mfma_f32_16x16x32_bf16 v[126:129], v[158:161], v[166:169], v[126:129]
	v_mfma_f32_16x16x32_bf16 v[106:109], v[154:157], v[170:173], 0
	v_mfma_f32_16x16x32_bf16 v[106:109], v[158:161], v[174:177], v[106:109]
	v_mfma_f32_16x16x32_bf16 v[110:113], v[146:149], v[170:173], 0
	v_mfma_f32_16x16x32_bf16 v[110:113], v[150:153], v[174:177], v[110:113]
	v_mfma_f32_16x16x32_bf16 v[118:121], v[114:117], v[170:173], 0
	v_mfma_f32_16x16x32_bf16 v[118:121], v[134:137], v[174:177], v[118:121]
	v_mfma_f32_16x16x32_bf16 v[122:125], v[74:77], v[170:173], 0
	v_mfma_f32_16x16x32_bf16 v[122:125], v[94:97], v[174:177], v[122:125]
	v_mfma_f32_16x16x32_bf16 v[102:105], v[74:77], v[188:191], 0
	v_mfma_f32_16x16x32_bf16 v[102:105], v[94:97], v[202:205], v[102:105]
	v_mfma_f32_16x16x32_bf16 v[98:101], v[114:117], v[188:191], 0
	v_mfma_f32_16x16x32_bf16 v[98:101], v[134:137], v[202:205], v[98:101]
	v_mfma_f32_16x16x32_bf16 v[90:93], v[146:149], v[188:191], 0
	v_mfma_f32_16x16x32_bf16 v[90:93], v[150:153], v[202:205], v[90:93]
	v_mfma_f32_16x16x32_bf16 v[86:89], v[154:157], v[188:191], 0
	v_mfma_f32_16x16x32_bf16 v[86:89], v[158:161], v[202:205], v[86:89]
	v_mfma_f32_16x16x32_bf16 v[66:69], v[154:157], v[206:209], 0
	v_mfma_f32_16x16x32_bf16 v[66:69], v[158:161], v[210:213], v[66:69]
	v_mfma_f32_16x16x32_bf16 v[70:73], v[146:149], v[206:209], 0
	v_mfma_f32_16x16x32_bf16 v[70:73], v[150:153], v[210:213], v[70:73]
	v_mfma_f32_16x16x32_bf16 v[78:81], v[114:117], v[206:209], 0
	v_mfma_f32_16x16x32_bf16 v[78:81], v[134:137], v[210:213], v[78:81]
	v_mfma_f32_16x16x32_bf16 v[82:85], v[74:77], v[206:209], 0
	v_mfma_f32_16x16x32_bf16 v[82:85], v[94:97], v[210:213], v[82:85]
	s_setprio 0
	s_barrier
	ds_read_b128 v[162:165], v186 offset:16384
	ds_read_b128 v[166:169], v186 offset:17408
	ds_read_b128 v[170:173], v186 offset:18432
	ds_read_b128 v[174:177], v186 offset:19456
	ds_read_b128 v[188:191], v186 offset:20480
	ds_read_b128 v[202:205], v186 offset:21504
	ds_read_b128 v[206:209], v186 offset:22528
	ds_read_b128 v[210:213], v186 offset:23552
	s_mov_b32 m0, s29
	s_nop 0
	global_load_lds_dwordx4 v180, s[58:59]
	s_add_u32 s30, s58, 0x40000
	s_mov_b32 m0, s42
	s_nop 0
	global_load_lds_dwordx4 v182, s[58:59]
	s_addc_u32 s31, s59, 0
	s_mov_b32 m0, s43
	s_nop 0
	global_load_lds_dwordx4 v180, s[30:31]
	s_nop 0
	s_mov_b32 m0, s44
	s_nop 0
	global_load_lds_dwordx4 v182, s[30:31]
	s_nop 0
	s_mov_b32 m0, s15
	s_nop 0
	global_load_lds_dwordx4 v0, s[60:61]
	s_nop 0
	s_mov_b32 m0, s45
	s_nop 0
	global_load_lds_dwordx4 v181, s[60:61]
	s_cmp_lg_u32 s85, 1
	s_cbranch_scc1 .Lpeel_pair_skipw
	s_waitcnt vmcnt(8)
; #define PG8_STAGE(bufoff, gbase, voff) do { _Pragma("unroll") for (int _i = 0; _i < 2; ++_i) { \
;         const unsigned _m0 = ldsb + (unsigned)((bufoff) + _i * 8192); const char* _gb = (const char*)(gbase); \
;         asm volatile("s_mov_b32 m0, %0\n\ts_nop 0\n\tglobal_load_lds_dwordx4 %1, %2" :: "s"(_m0), "v"((voff)[_i]), "s"(_gb) : "m0", "memory"); } } while (0)
; #define PG8_LDA(dst, b, h) do { _Pragma("unroll") for (int m = 0; m < 4; ++m) _Pragma("unroll") for (int k = 0; k < 2; ++k) dst[m][k] = *(const LAS bf16x8*)(lds + PG8_SA(b, h) + aoff + m * 2048 + k * 1024); } while (0)
; #define PG8_LDB(dst, b, h) do { _Pragma("unroll") for (int n = 0; n < 2; ++n) _Pragma("unroll") for (int k = 0; k < 2; ++k) dst[n][k] = *(const LAS bf16x8*)(lds + PG8_SB(b, h) + boff + n * 2048 + k * 1024); } while (0)
; #define PG8_MMA(ai, bj, At, Bt) do { __builtin_amdgcn_s_setprio(1); _Pragma("unroll") for (int m = 0; m < 4; ++m) _Pragma("unroll") for (int n = 0; n < 2; ++n) _Pragma("unroll") for (int k = 0; k < 2; ++k) \
;         acc[ai][bj][m][n] = __builtin_amdgcn_mfma_f32_16x16x32_bf16(Bt[n][k], At[m][k], acc[ai][bj][m][n], 0, 0, 0); __builtin_amdgcn_s_setprio(0); } while (0)
; #define PG8_WAIT_V(n) asm volatile("s_waitcnt vmcnt(" #n ")" ::: "memory")
; #define PG8_WAIT_L(n) asm volatile("s_waitcnt lgkmcnt(" #n ")" ::: "memory")
; #define PG8_BAR __builtin_amdgcn_s_barrier()
; #define PG8_SCHED __builtin_amdgcn_sched_barrier(0)
; template <class Epi, bool ALIGN_EPI>
; __device__ __forceinline__ void gemm_phase(LAS unsigned char* lds, const Gemm g, const StaticOrder& S, const Epi& E) {
;     ...
;             PG8_WAIT_V(8); PG8_WAIT_L(0); PG8_BAR; PG8_MMA(1, 0, At, B0); PG8_MMA(1, 1, At, B1); PG8_BAR; PG8_SCHED;
;             PG8_LDB(B0, 1, 0); PG8_LDB(B1, 1, 1); PG8_SCHED; PG8_LDA(At, 1, 0); PG8_STAGE(PG8_SA(0, 1), a2 + hstepA, voffA);
;             PG8_WAIT_V(8); PG8_WAIT_L(0); PG8_BAR; PG8_MMA(0, 0, At, B0); PG8_MMA(0, 1, At, B1); PG8_BAR; PG8_SCHED;
;             PG8_LDA(At, 1, 1); PG8_STAGE(PG8_SB(1, 0), b3, voffB); PG8_STAGE(PG8_SB(1, 1), b3 + hstepB, voffB); PG8_STAGE(PG8_SA(1, 0), a3, voffA);
;             PG8_WAIT_V(8); PG8_WAIT_L(0); PG8_BAR; PG8_MMA(1, 0, At, B0); PG8_MMA(1, 1, At, B1); PG8_BAR; PG8_SCHED;
.Lpeel_pair_skipw:
	s_waitcnt lgkmcnt(0)
	s_barrier
	s_setprio 1
	s_waitcnt lgkmcnt(0)
	v_mfma_f32_16x16x32_bf16 v[62:65], v[74:77], v[162:165], 0
	v_mfma_f32_16x16x32_bf16 v[62:65], v[94:97], v[166:169], v[62:65]
	v_mfma_f32_16x16x32_bf16 v[58:61], v[114:117], v[162:165], 0
	v_mfma_f32_16x16x32_bf16 v[58:61], v[134:137], v[166:169], v[58:61]
	v_mfma_f32_16x16x32_bf16 v[54:57], v[146:149], v[162:165], 0
	v_mfma_f32_16x16x32_bf16 v[54:57], v[150:153], v[166:169], v[54:57]
	v_mfma_f32_16x16x32_bf16 v[50:53], v[154:157], v[162:165], 0
	v_mfma_f32_16x16x32_bf16 v[50:53], v[158:161], v[166:169], v[50:53]
	v_mfma_f32_16x16x32_bf16 v[34:37], v[154:157], v[170:173], 0
	v_mfma_f32_16x16x32_bf16 v[34:37], v[158:161], v[174:177], v[34:37]
	v_mfma_f32_16x16x32_bf16 v[38:41], v[146:149], v[170:173], 0
	v_mfma_f32_16x16x32_bf16 v[38:41], v[150:153], v[174:177], v[38:41]
	v_mfma_f32_16x16x32_bf16 v[42:45], v[114:117], v[170:173], 0
	v_mfma_f32_16x16x32_bf16 v[42:45], v[134:137], v[174:177], v[42:45]
	v_mfma_f32_16x16x32_bf16 v[46:49], v[74:77], v[170:173], 0
	v_mfma_f32_16x16x32_bf16 v[46:49], v[94:97], v[174:177], v[46:49]
	v_mfma_f32_16x16x32_bf16 v[30:33], v[74:77], v[188:191], 0
	v_mfma_f32_16x16x32_bf16 v[30:33], v[94:97], v[202:205], v[30:33]
	v_mfma_f32_16x16x32_bf16 v[26:29], v[114:117], v[188:191], 0
	v_mfma_f32_16x16x32_bf16 v[26:29], v[134:137], v[202:205], v[26:29]
	v_mfma_f32_16x16x32_bf16 v[22:25], v[146:149], v[188:191], 0
	v_mfma_f32_16x16x32_bf16 v[22:25], v[150:153], v[202:205], v[22:25]
	v_mfma_f32_16x16x32_bf16 v[18:21], v[154:157], v[188:191], 0
	v_mfma_f32_16x16x32_bf16 v[18:21], v[158:161], v[202:205], v[18:21]
	v_mfma_f32_16x16x32_bf16 v[2:5], v[154:157], v[206:209], 0
	v_mfma_f32_16x16x32_bf16 v[2:5], v[158:161], v[210:213], v[2:5]
	v_mfma_f32_16x16x32_bf16 v[6:9], v[146:149], v[206:209], 0
	v_mfma_f32_16x16x32_bf16 v[6:9], v[150:153], v[210:213], v[6:9]
	v_mfma_f32_16x16x32_bf16 v[10:13], v[114:117], v[206:209], 0
	v_mfma_f32_16x16x32_bf16 v[10:13], v[134:137], v[210:213], v[10:13]
	v_mfma_f32_16x16x32_bf16 v[14:17], v[74:77], v[206:209], 0
	v_mfma_f32_16x16x32_bf16 v[14:17], v[94:97], v[210:213], v[14:17]
	s_setprio 0
	s_barrier
	v_add_u32_e32 v134, 0x18000, v185
	v_add_u32_e32 v158, 0x1c000, v185
	ds_read_b128 v[74:77], v134
	ds_read_b128 v[94:97], v134 offset:1024
	ds_read_b128 v[114:117], v134 offset:2048
	ds_read_b128 v[134:137], v134 offset:3072
	ds_read_b128 v[146:149], v158
	ds_read_b128 v[150:153], v158 offset:1024
	ds_read_b128 v[154:157], v158 offset:2048
	ds_read_b128 v[158:161], v158 offset:3072
	ds_read_b128 v[162:165], v186 offset:32768
	ds_read_b128 v[166:169], v186 offset:33792
	ds_read_b128 v[170:173], v186 offset:34816
	ds_read_b128 v[174:177], v186 offset:35840
	ds_read_b128 v[188:191], v186 offset:36864
	ds_read_b128 v[202:205], v186 offset:37888
	ds_read_b128 v[206:209], v186 offset:38912
	ds_read_b128 v[210:213], v186 offset:39936
	s_add_u32 s30, s60, 0x40000
	s_addc_u32 s31, s61, 0
	s_mov_b32 m0, s55
	s_nop 0
	global_load_lds_dwordx4 v0, s[30:31]
	s_nop 0
	s_mov_b32 m0, s88
	s_nop 0
	global_load_lds_dwordx4 v181, s[30:31]
	s_waitcnt vmcnt(8)
	s_waitcnt lgkmcnt(0)
	s_barrier
	s_setprio 1
	s_waitcnt lgkmcnt(0)
	v_mfma_f32_16x16x32_bf16 v[142:145], v[74:77], v[162:165], v[142:145]
	v_mfma_f32_16x16x32_bf16 v[142:145], v[94:97], v[166:169], v[142:145]
	v_mfma_f32_16x16x32_bf16 v[138:141], v[114:117], v[162:165], v[138:141]
	v_mfma_f32_16x16x32_bf16 v[138:141], v[134:137], v[166:169], v[138:141]
	v_mfma_f32_16x16x32_bf16 v[130:133], v[146:149], v[162:165], v[130:133]
	v_mfma_f32_16x16x32_bf16 v[130:133], v[150:153], v[166:169], v[130:133]
	v_mfma_f32_16x16x32_bf16 v[126:129], v[154:157], v[162:165], v[126:129]
	v_mfma_f32_16x16x32_bf16 v[126:129], v[158:161], v[166:169], v[126:129]
	v_mfma_f32_16x16x32_bf16 v[106:109], v[154:157], v[170:173], v[106:109]
	v_mfma_f32_16x16x32_bf16 v[106:109], v[158:161], v[174:177], v[106:109]
	v_mfma_f32_16x16x32_bf16 v[110:113], v[146:149], v[170:173], v[110:113]
	v_mfma_f32_16x16x32_bf16 v[110:113], v[150:153], v[174:177], v[110:113]
	v_mfma_f32_16x16x32_bf16 v[118:121], v[114:117], v[170:173], v[118:121]
	v_mfma_f32_16x16x32_bf16 v[118:121], v[134:137], v[174:177], v[118:121]
	v_mfma_f32_16x16x32_bf16 v[122:125], v[74:77], v[170:173], v[122:125]
	v_mfma_f32_16x16x32_bf16 v[122:125], v[94:97], v[174:177], v[122:125]
	v_mfma_f32_16x16x32_bf16 v[102:105], v[74:77], v[188:191], v[102:105]
	v_mfma_f32_16x16x32_bf16 v[102:105], v[94:97], v[202:205], v[102:105]
	v_mfma_f32_16x16x32_bf16 v[98:101], v[114:117], v[188:191], v[98:101]
	v_mfma_f32_16x16x32_bf16 v[98:101], v[134:137], v[202:205], v[98:101]
	v_mfma_f32_16x16x32_bf16 v[90:93], v[146:149], v[188:191], v[90:93]
	v_mfma_f32_16x16x32_bf16 v[90:93], v[150:153], v[202:205], v[90:93]
	v_mfma_f32_16x16x32_bf16 v[86:89], v[154:157], v[188:191], v[86:89]
	v_mfma_f32_16x16x32_bf16 v[86:89], v[158:161], v[202:205], v[86:89]
	v_mfma_f32_16x16x32_bf16 v[66:69], v[154:157], v[206:209], v[66:69]
	v_mfma_f32_16x16x32_bf16 v[66:69], v[158:161], v[210:213], v[66:69]
	v_mfma_f32_16x16x32_bf16 v[70:73], v[146:149], v[206:209], v[70:73]
	v_mfma_f32_16x16x32_bf16 v[70:73], v[150:153], v[210:213], v[70:73]
	v_mfma_f32_16x16x32_bf16 v[78:81], v[114:117], v[206:209], v[78:81]
	v_mfma_f32_16x16x32_bf16 v[78:81], v[134:137], v[210:213], v[78:81]
	v_mfma_f32_16x16x32_bf16 v[82:85], v[74:77], v[206:209], v[82:85]
	v_mfma_f32_16x16x32_bf16 v[82:85], v[94:97], v[210:213], v[82:85]
	s_setprio 0
	s_barrier
; #define PG8_STAGE(bufoff, gbase, voff) do { _Pragma("unroll") for (int _i = 0; _i < 2; ++_i) { \
;         const unsigned _m0 = ldsb + (unsigned)((bufoff) + _i * 8192); const char* _gb = (const char*)(gbase); \
;         asm volatile("s_mov_b32 m0, %0\n\ts_nop 0\n\tglobal_load_lds_dwordx4 %1, %2" :: "s"(_m0), "v"((voff)[_i]), "s"(_gb) : "m0", "memory"); } } while (0)
; #define PG8_LDA(dst, b, h) do { _Pragma("unroll") for (int m = 0; m < 4; ++m) _Pragma("unroll") for (int k = 0; k < 2; ++k) dst[m][k] = *(const LAS bf16x8*)(lds + PG8_SA(b, h) + aoff + m * 2048 + k * 1024); } while (0)
; #define PG8_MMA(ai, bj, At, Bt) do { __builtin_amdgcn_s_setprio(1); _Pragma("unroll") for (int m = 0; m < 4; ++m) _Pragma("unroll") for (int n = 0; n < 2; ++n) _Pragma("unroll") for (int k = 0; k < 2; ++k) \
;         acc[ai][bj][m][n] = __builtin_amdgcn_mfma_f32_16x16x32_bf16(Bt[n][k], At[m][k], acc[ai][bj][m][n], 0, 0, 0); __builtin_amdgcn_s_setprio(0); } while (0)
; #define PG8_WAIT_V(n) asm volatile("s_waitcnt vmcnt(" #n ")" ::: "memory")
; #define PG8_WAIT_L(n) asm volatile("s_waitcnt lgkmcnt(" #n ")" ::: "memory")
; #define PG8_BAR __builtin_amdgcn_s_barrier()
; #define PG8_SCHED __builtin_amdgcn_sched_barrier(0)
; template <class Epi, bool ALIGN_EPI>
; __device__ __forceinline__ void gemm_phase(LAS unsigned char* lds, const Gemm g, const StaticOrder& S, const Epi& E) {
;     ...
;             PG8_LDA(At, 1, 1); PG8_STAGE(PG8_SB(1, 0), b3, voffB); PG8_STAGE(PG8_SB(1, 1), b3 + hstepB, voffB); PG8_STAGE(PG8_SA(1, 0), a3, voffA);
;             PG8_WAIT_V(8); PG8_WAIT_L(0); PG8_BAR; PG8_MMA(1, 0, At, B0); PG8_MMA(1, 1, At, B1); PG8_BAR; PG8_SCHED;
;         }
	ds_read_b128 v[162:165], v186 offset:49152
	ds_read_b128 v[166:169], v186 offset:50176
	ds_read_b128 v[170:173], v186 offset:51200
	ds_read_b128 v[174:177], v186 offset:52224
	ds_read_b128 v[188:191], v186 offset:53248
	ds_read_b128 v[202:205], v186 offset:54272
	ds_read_b128 v[206:209], v186 offset:55296
	ds_read_b128 v[210:213], v186 offset:56320
	s_add_u32 s30, s58, 0x80
	s_addc_u32 s31, s59, 0
	s_mov_b32 m0, s94
	s_nop 0
	global_load_lds_dwordx4 v180, s[30:31]
	s_nop 0
	s_mov_b32 m0, s95
	s_nop 0
	global_load_lds_dwordx4 v182, s[30:31]
	s_add_u32 s30, s58, 0x40080
	s_addc_u32 s31, s59, 0
	s_mov_b32 m0, s17
	s_nop 0
	global_load_lds_dwordx4 v180, s[30:31]
	s_nop 0
	s_mov_b32 m0, s53
	s_nop 0
	global_load_lds_dwordx4 v182, s[30:31]
	s_nop 0
	s_mov_b32 m0, s96
	s_nop 0
	global_load_lds_dwordx4 v0, s[56:57]
	s_nop 0
	s_mov_b32 m0, s97
	s_nop 0
	global_load_lds_dwordx4 v181, s[56:57]
	s_waitcnt vmcnt(8)
	s_waitcnt lgkmcnt(0)
	s_barrier
	s_setprio 1
	s_waitcnt lgkmcnt(0)
	v_mfma_f32_16x16x32_bf16 v[62:65], v[74:77], v[162:165], v[62:65]
	v_mfma_f32_16x16x32_bf16 v[62:65], v[94:97], v[166:169], v[62:65]
	v_mfma_f32_16x16x32_bf16 v[58:61], v[114:117], v[162:165], v[58:61]
	v_mfma_f32_16x16x32_bf16 v[58:61], v[134:137], v[166:169], v[58:61]
	v_mfma_f32_16x16x32_bf16 v[54:57], v[146:149], v[162:165], v[54:57]
	v_mfma_f32_16x16x32_bf16 v[54:57], v[150:153], v[166:169], v[54:57]
	v_mfma_f32_16x16x32_bf16 v[50:53], v[154:157], v[162:165], v[50:53]
	v_mfma_f32_16x16x32_bf16 v[50:53], v[158:161], v[166:169], v[50:53]
	v_mfma_f32_16x16x32_bf16 v[34:37], v[154:157], v[170:173], v[34:37]
	v_mfma_f32_16x16x32_bf16 v[34:37], v[158:161], v[174:177], v[34:37]
	v_mfma_f32_16x16x32_bf16 v[38:41], v[146:149], v[170:173], v[38:41]
	v_mfma_f32_16x16x32_bf16 v[38:41], v[150:153], v[174:177], v[38:41]
	v_mfma_f32_16x16x32_bf16 v[42:45], v[114:117], v[170:173], v[42:45]
	v_mfma_f32_16x16x32_bf16 v[42:45], v[134:137], v[174:177], v[42:45]
	v_mfma_f32_16x16x32_bf16 v[46:49], v[74:77], v[170:173], v[46:49]
	v_mfma_f32_16x16x32_bf16 v[46:49], v[94:97], v[174:177], v[46:49]
	v_mfma_f32_16x16x32_bf16 v[30:33], v[74:77], v[188:191], v[30:33]
	v_mfma_f32_16x16x32_bf16 v[30:33], v[94:97], v[202:205], v[30:33]
	v_mfma_f32_16x16x32_bf16 v[26:29], v[114:117], v[188:191], v[26:29]
	v_mfma_f32_16x16x32_bf16 v[26:29], v[134:137], v[202:205], v[26:29]
	v_mfma_f32_16x16x32_bf16 v[22:25], v[146:149], v[188:191], v[22:25]
	v_mfma_f32_16x16x32_bf16 v[22:25], v[150:153], v[202:205], v[22:25]
	v_mfma_f32_16x16x32_bf16 v[18:21], v[154:157], v[188:191], v[18:21]
	v_mfma_f32_16x16x32_bf16 v[18:21], v[158:161], v[202:205], v[18:21]
	v_mfma_f32_16x16x32_bf16 v[2:5], v[154:157], v[206:209], v[2:5]
	v_mfma_f32_16x16x32_bf16 v[2:5], v[158:161], v[210:213], v[2:5]
	v_mfma_f32_16x16x32_bf16 v[6:9], v[146:149], v[206:209], v[6:9]
	v_mfma_f32_16x16x32_bf16 v[6:9], v[150:153], v[210:213], v[6:9]
	v_mfma_f32_16x16x32_bf16 v[10:13], v[114:117], v[206:209], v[10:13]
	v_mfma_f32_16x16x32_bf16 v[10:13], v[134:137], v[210:213], v[10:13]
	v_mfma_f32_16x16x32_bf16 v[14:17], v[74:77], v[206:209], v[14:17]
	v_mfma_f32_16x16x32_bf16 v[14:17], v[94:97], v[210:213], v[14:17]
	s_setprio 0
	s_barrier
	s_add_i32 s50, s50, 2
	s_add_u32 s41, s41, 0x100
	s_addc_u32 s49, s49, 0
	s_add_u32 s92, s92, 0x100
	s_addc_u32 s93, s93, 0
	s_cmp_gt_u32 s50, 13

; __device__ __forceinline__ unsigned cvt_pk_bf16(float lo, float hi) { unsigned r; asm volatile("v_cvt_pk_bf16_f32 %0, %1, %2" : "=v"(r) : "v"(lo), "v"(hi)); return r; }
; __device__ __forceinline__ float silu_f(float g) { return g * __builtin_amdgcn_rcpf(1.0f + __builtin_amdgcn_exp2f(g * -1.4426950408889634f)); }
;     __device__ __forceinline__ void operator()(const f32x4 (&acc)[2][2][4][2], const Unit& u, int wr, int wc, int fr, int fq) const {
;     ...
;             for (int m = 0; m < 4; ++m) { const int row = row0 + ai * HALF + m * 16; const float rs = rsv[ai][m];
;                 f32x4 g0 = acc[ai][0][m][0] * rs, g1 = acc[ai][0][m][1] * rs; const f32x4 t0 = acc[ai][1][m][0] * rs, t1 = acc[ai][1][m][1] * rs;
;                 if (silu) {
; #pragma unroll
;                     for (int j = 0; j < 4; ++j) { g0[j] = silu_f(g0[j]); g1[j] = silu_f(g1[j]); } }
;                 g0 = g0 * t0; g1 = g1 * t1;
;                 u32x4 w; w.x = cvt_pk_bf16(g0[0], g0[1]); w.y = cvt_pk_bf16(g0[2], g0[3]); w.z = cvt_pk_bf16(g1[0], g1[1]); w.w = cvt_pk_bf16(g1[2], g1[3]);
;                 *(u32x4*)(O + (size_t)row * ldc + col0 + (size_t)(row >> 12) * adj) = w; }
.Lep_have_rs:
	v_pk_mul_f32 v[146:147], v[142:143], v[240:241] op_sel_hi:[1,0]
	v_pk_mul_f32 v[148:149], v[144:145], v[240:241] op_sel_hi:[1,0]
	v_pk_mul_f32 v[150:151], v[138:139], v[240:241] op_sel_hi:[1,0]
	v_pk_mul_f32 v[152:153], v[140:141], v[240:241] op_sel_hi:[1,0]
	v_exp_f32_e32 v146, v146
	v_exp_f32_e32 v147, v147
	v_exp_f32_e32 v148, v148
	v_exp_f32_e32 v149, v149
	v_exp_f32_e32 v150, v150
	v_exp_f32_e32 v151, v151
	v_exp_f32_e32 v152, v152
	v_exp_f32_e32 v153, v153
	v_pk_mul_f32 v[142:143], v[142:143], v[130:131]
	v_pk_mul_f32 v[144:145], v[144:145], v[132:133]
	v_pk_mul_f32 v[138:139], v[138:139], v[126:127]
	v_pk_mul_f32 v[140:141], v[140:141], v[128:129]
	v_pk_fma_f32 v[146:147], v[146:147], v[240:241], v[240:241] op_sel:[0,1,1] op_sel_hi:[1,1,1]
	v_pk_fma_f32 v[148:149], v[148:149], v[240:241], v[240:241] op_sel:[0,1,1] op_sel_hi:[1,1,1]
	v_pk_fma_f32 v[150:151], v[150:151], v[240:241], v[240:241] op_sel:[0,1,1] op_sel_hi:[1,1,1]
	v_pk_fma_f32 v[152:153], v[152:153], v[240:241], v[240:241] op_sel:[0,1,1] op_sel_hi:[1,1,1]
	v_rcp_f32_e32 v146, v146
	v_rcp_f32_e32 v147, v147
	v_rcp_f32_e32 v148, v148
	v_rcp_f32_e32 v149, v149
	v_rcp_f32_e32 v150, v150
	v_rcp_f32_e32 v151, v151
	v_rcp_f32_e32 v152, v152
	v_rcp_f32_e32 v153, v153
	v_pk_mul_f32 v[154:155], v[122:123], v[242:243] op_sel_hi:[1,0]
	v_pk_mul_f32 v[156:157], v[124:125], v[242:243] op_sel_hi:[1,0]
	v_pk_mul_f32 v[158:159], v[118:119], v[242:243] op_sel_hi:[1,0]
	v_pk_mul_f32 v[160:161], v[120:121], v[242:243] op_sel_hi:[1,0]
	v_pk_mul_f32 v[142:143], v[142:143], v[146:147]
	v_pk_mul_f32 v[144:145], v[144:145], v[148:149]
	v_pk_mul_f32 v[138:139], v[138:139], v[150:151]
	v_pk_mul_f32 v[140:141], v[140:141], v[152:153]
	v_cvt_pk_bf16_f32 v162, v142, v143
	v_cvt_pk_bf16_f32 v163, v144, v145
	v_cvt_pk_bf16_f32 v164, v138, v139
	v_cvt_pk_bf16_f32 v165, v140, v141
	v_exp_f32_e32 v154, v154
	v_exp_f32_e32 v155, v155
	v_exp_f32_e32 v156, v156
	v_exp_f32_e32 v157, v157
	v_exp_f32_e32 v158, v158
	v_exp_f32_e32 v159, v159
	v_exp_f32_e32 v160, v160
	v_exp_f32_e32 v161, v161
	v_pk_mul_f32 v[122:123], v[122:123], v[110:111]
	v_pk_mul_f32 v[124:125], v[124:125], v[112:113]
	v_pk_mul_f32 v[118:119], v[118:119], v[106:107]
	v_pk_mul_f32 v[120:121], v[120:121], v[108:109]
	v_pk_fma_f32 v[154:155], v[154:155], v[242:243], v[242:243] op_sel:[0,1,1] op_sel_hi:[1,1,1]
	v_pk_fma_f32 v[156:157], v[156:157], v[242:243], v[242:243] op_sel:[0,1,1] op_sel_hi:[1,1,1]
	v_pk_fma_f32 v[158:159], v[158:159], v[242:243], v[242:243] op_sel:[0,1,1] op_sel_hi:[1,1,1]
	v_pk_fma_f32 v[160:161], v[160:161], v[242:243], v[242:243] op_sel:[0,1,1] op_sel_hi:[1,1,1]
	v_rcp_f32_e32 v154, v154
	v_rcp_f32_e32 v155, v155
	v_rcp_f32_e32 v156, v156
	v_rcp_f32_e32 v157, v157
	v_rcp_f32_e32 v158, v158
	v_rcp_f32_e32 v159, v159
	v_rcp_f32_e32 v160, v160
	v_rcp_f32_e32 v161, v161
	v_pk_mul_f32 v[146:147], v[102:103], v[244:245] op_sel_hi:[1,0]
	v_pk_mul_f32 v[148:149], v[104:105], v[244:245] op_sel_hi:[1,0]
	v_pk_mul_f32 v[150:151], v[98:99], v[244:245] op_sel_hi:[1,0]
	v_pk_mul_f32 v[152:153], v[100:101], v[244:245] op_sel_hi:[1,0]
	v_pk_mul_f32 v[122:123], v[122:123], v[154:155]
	v_pk_mul_f32 v[124:125], v[124:125], v[156:157]
	v_pk_mul_f32 v[118:119], v[118:119], v[158:159]
	v_pk_mul_f32 v[120:121], v[120:121], v[160:161]
	v_cvt_pk_bf16_f32 v166, v122, v123
	v_cvt_pk_bf16_f32 v167, v124, v125
	v_cvt_pk_bf16_f32 v168, v118, v119
	v_cvt_pk_bf16_f32 v169, v120, v121
	v_exp_f32_e32 v146, v146
	v_exp_f32_e32 v147, v147
	v_exp_f32_e32 v148, v148
	v_exp_f32_e32 v149, v149
	v_exp_f32_e32 v150, v150
	v_exp_f32_e32 v151, v151
	v_exp_f32_e32 v152, v152
	v_exp_f32_e32 v153, v153
	v_pk_mul_f32 v[102:103], v[102:103], v[90:91]
	v_pk_mul_f32 v[104:105], v[104:105], v[92:93]
	v_pk_mul_f32 v[98:99], v[98:99], v[86:87]
	v_pk_mul_f32 v[100:101], v[100:101], v[88:89]
	v_pk_fma_f32 v[146:147], v[146:147], v[244:245], v[244:245] op_sel:[0,1,1] op_sel_hi:[1,1,1]
	v_pk_fma_f32 v[148:149], v[148:149], v[244:245], v[244:245] op_sel:[0,1,1] op_sel_hi:[1,1,1]
	v_pk_fma_f32 v[150:151], v[150:151], v[244:245], v[244:245] op_sel:[0,1,1] op_sel_hi:[1,1,1]
	v_pk_fma_f32 v[152:153], v[152:153], v[244:245], v[244:245] op_sel:[0,1,1] op_sel_hi:[1,1,1]
	v_rcp_f32_e32 v146, v146
	v_rcp_f32_e32 v147, v147
	v_rcp_f32_e32 v148, v148
	v_rcp_f32_e32 v149, v149
	v_rcp_f32_e32 v150, v150
	v_rcp_f32_e32 v151, v151
	v_rcp_f32_e32 v152, v152
	v_rcp_f32_e32 v153, v153
	v_pk_mul_f32 v[154:155], v[82:83], v[246:247] op_sel_hi:[1,0]
	v_pk_mul_f32 v[156:157], v[84:85], v[246:247] op_sel_hi:[1,0]
	v_pk_mul_f32 v[158:159], v[78:79], v[246:247] op_sel_hi:[1,0]
	v_pk_mul_f32 v[160:161], v[80:81], v[246:247] op_sel_hi:[1,0]
	v_pk_mul_f32 v[102:103], v[102:103], v[146:147]
	v_pk_mul_f32 v[104:105], v[104:105], v[148:149]
	v_pk_mul_f32 v[98:99], v[98:99], v[150:151]
	v_pk_mul_f32 v[100:101], v[100:101], v[152:153]
	v_cvt_pk_bf16_f32 v170, v102, v103
	v_cvt_pk_bf16_f32 v171, v104, v105
	v_cvt_pk_bf16_f32 v172, v98, v99
	v_cvt_pk_bf16_f32 v173, v100, v101
	v_exp_f32_e32 v154, v154
	v_exp_f32_e32 v155, v155
	v_exp_f32_e32 v156, v156
	v_exp_f32_e32 v157, v157
	v_exp_f32_e32 v158, v158
	v_exp_f32_e32 v159, v159
	v_exp_f32_e32 v160, v160
	v_exp_f32_e32 v161, v161
	v_pk_mul_f32 v[82:83], v[82:83], v[70:71]
	v_pk_mul_f32 v[84:85], v[84:85], v[72:73]
	v_pk_mul_f32 v[78:79], v[78:79], v[66:67]
	v_pk_mul_f32 v[80:81], v[80:81], v[68:69]
	v_pk_fma_f32 v[154:155], v[154:155], v[246:247], v[246:247] op_sel:[0,1,1] op_sel_hi:[1,1,1]
	v_pk_fma_f32 v[156:157], v[156:157], v[246:247], v[246:247] op_sel:[0,1,1] op_sel_hi:[1,1,1]
	v_pk_fma_f32 v[158:159], v[158:159], v[246:247], v[246:247] op_sel:[0,1,1] op_sel_hi:[1,1,1]
; __device__ __forceinline__ unsigned cvt_pk_bf16(float lo, float hi) { unsigned r; asm volatile("v_cvt_pk_bf16_f32 %0, %1, %2" : "=v"(r) : "v"(lo), "v"(hi)); return r; }
; __device__ __forceinline__ float silu_f(float g) { return g * __builtin_amdgcn_rcpf(1.0f + __builtin_amdgcn_exp2f(g * -1.4426950408889634f)); }
;     __device__ __forceinline__ void operator()(const f32x4 (&acc)[2][2][4][2], const Unit& u, int wr, int wc, int fr, int fq) const {
;     ...
;             for (int m = 0; m < 4; ++m) { const int row = row0 + ai * HALF + m * 16; const float rs = rsv[ai][m];
;                 f32x4 g0 = acc[ai][0][m][0] * rs, g1 = acc[ai][0][m][1] * rs; const f32x4 t0 = acc[ai][1][m][0] * rs, t1 = acc[ai][1][m][1] * rs;
;                 if (silu) {
; #pragma unroll
;                     for (int j = 0; j < 4; ++j) { g0[j] = silu_f(g0[j]); g1[j] = silu_f(g1[j]); } }
;                 g0 = g0 * t0; g1 = g1 * t1;
;                 u32x4 w; w.x = cvt_pk_bf16(g0[0], g0[1]); w.y = cvt_pk_bf16(g0[2], g0[3]); w.z = cvt_pk_bf16(g1[0], g1[1]); w.w = cvt_pk_bf16(g1[2], g1[3]);
;                 *(u32x4*)(O + (size_t)row * ldc + col0 + (size_t)(row >> 12) * adj) = w; }
	v_pk_fma_f32 v[160:161], v[160:161], v[246:247], v[246:247] op_sel:[0,1,1] op_sel_hi:[1,1,1]
	v_rcp_f32_e32 v154, v154
	v_rcp_f32_e32 v155, v155
	v_rcp_f32_e32 v156, v156
	v_rcp_f32_e32 v157, v157
	v_rcp_f32_e32 v158, v158
	v_rcp_f32_e32 v159, v159
	v_rcp_f32_e32 v160, v160
	v_rcp_f32_e32 v161, v161
	v_pk_mul_f32 v[146:147], v[62:63], v[248:249] op_sel_hi:[1,0]
	v_pk_mul_f32 v[148:149], v[64:65], v[248:249] op_sel_hi:[1,0]
	v_pk_mul_f32 v[150:151], v[58:59], v[248:249] op_sel_hi:[1,0]
	v_pk_mul_f32 v[152:153], v[60:61], v[248:249] op_sel_hi:[1,0]
	v_pk_mul_f32 v[82:83], v[82:83], v[154:155]
	v_pk_mul_f32 v[84:85], v[84:85], v[156:157]
	v_pk_mul_f32 v[78:79], v[78:79], v[158:159]
	v_pk_mul_f32 v[80:81], v[80:81], v[160:161]
	v_cvt_pk_bf16_f32 v174, v82, v83
	v_cvt_pk_bf16_f32 v175, v84, v85
	v_cvt_pk_bf16_f32 v176, v78, v79
	v_cvt_pk_bf16_f32 v177, v80, v81
	v_exp_f32_e32 v146, v146
	v_exp_f32_e32 v147, v147
	v_exp_f32_e32 v148, v148
	v_exp_f32_e32 v149, v149
	v_exp_f32_e32 v150, v150
	v_exp_f32_e32 v151, v151
	v_exp_f32_e32 v152, v152
	v_exp_f32_e32 v153, v153
	v_pk_mul_f32 v[62:63], v[62:63], v[54:55]
	v_pk_mul_f32 v[64:65], v[64:65], v[56:57]
	v_pk_mul_f32 v[58:59], v[58:59], v[50:51]
	v_pk_mul_f32 v[60:61], v[60:61], v[52:53]
	v_pk_fma_f32 v[146:147], v[146:147], v[248:249], v[248:249] op_sel:[0,1,1] op_sel_hi:[1,1,1]
	v_pk_fma_f32 v[148:149], v[148:149], v[248:249], v[248:249] op_sel:[0,1,1] op_sel_hi:[1,1,1]
	v_pk_fma_f32 v[150:151], v[150:151], v[248:249], v[248:249] op_sel:[0,1,1] op_sel_hi:[1,1,1]
	v_pk_fma_f32 v[152:153], v[152:153], v[248:249], v[248:249] op_sel:[0,1,1] op_sel_hi:[1,1,1]
	v_rcp_f32_e32 v146, v146
	v_rcp_f32_e32 v147, v147
	v_rcp_f32_e32 v148, v148
	v_rcp_f32_e32 v149, v149
	v_rcp_f32_e32 v150, v150
	v_rcp_f32_e32 v151, v151
	v_rcp_f32_e32 v152, v152
	v_rcp_f32_e32 v153, v153
	v_pk_mul_f32 v[154:155], v[46:47], v[250:251] op_sel_hi:[1,0]
	v_pk_mul_f32 v[156:157], v[48:49], v[250:251] op_sel_hi:[1,0]
	v_pk_mul_f32 v[158:159], v[42:43], v[250:251] op_sel_hi:[1,0]
	v_pk_mul_f32 v[160:161], v[44:45], v[250:251] op_sel_hi:[1,0]
	v_pk_mul_f32 v[62:63], v[62:63], v[146:147]
	v_pk_mul_f32 v[64:65], v[64:65], v[148:149]
	v_pk_mul_f32 v[58:59], v[58:59], v[150:151]
	v_pk_mul_f32 v[60:61], v[60:61], v[152:153]
	v_cvt_pk_bf16_f32 v202, v62, v63
	v_cvt_pk_bf16_f32 v203, v64, v65
	v_cvt_pk_bf16_f32 v204, v58, v59
	v_cvt_pk_bf16_f32 v205, v60, v61
	v_exp_f32_e32 v154, v154
	v_exp_f32_e32 v155, v155
	v_exp_f32_e32 v156, v156
	v_exp_f32_e32 v157, v157
	v_exp_f32_e32 v158, v158
	v_exp_f32_e32 v159, v159
	v_exp_f32_e32 v160, v160
	v_exp_f32_e32 v161, v161
	v_pk_mul_f32 v[46:47], v[46:47], v[38:39]
	v_pk_mul_f32 v[48:49], v[48:49], v[40:41]
	v_pk_mul_f32 v[42:43], v[42:43], v[34:35]
	v_pk_mul_f32 v[44:45], v[44:45], v[36:37]
	v_pk_fma_f32 v[154:155], v[154:155], v[250:251], v[250:251] op_sel:[0,1,1] op_sel_hi:[1,1,1]
	v_pk_fma_f32 v[156:157], v[156:157], v[250:251], v[250:251] op_sel:[0,1,1] op_sel_hi:[1,1,1]
	v_pk_fma_f32 v[158:159], v[158:159], v[250:251], v[250:251] op_sel:[0,1,1] op_sel_hi:[1,1,1]
	v_pk_fma_f32 v[160:161], v[160:161], v[250:251], v[250:251] op_sel:[0,1,1] op_sel_hi:[1,1,1]
	v_rcp_f32_e32 v154, v154
	v_rcp_f32_e32 v155, v155
	v_rcp_f32_e32 v156, v156
	v_rcp_f32_e32 v157, v157
	v_rcp_f32_e32 v158, v158
	v_rcp_f32_e32 v159, v159
	v_rcp_f32_e32 v160, v160
	v_rcp_f32_e32 v161, v161
	v_pk_mul_f32 v[146:147], v[30:31], v[252:253] op_sel_hi:[1,0]
	v_pk_mul_f32 v[148:149], v[32:33], v[252:253] op_sel_hi:[1,0]
	v_pk_mul_f32 v[150:151], v[26:27], v[252:253] op_sel_hi:[1,0]
	v_pk_mul_f32 v[152:153], v[28:29], v[252:253] op_sel_hi:[1,0]
	v_pk_mul_f32 v[46:47], v[46:47], v[154:155]
	v_pk_mul_f32 v[48:49], v[48:49], v[156:157]
	v_pk_mul_f32 v[42:43], v[42:43], v[158:159]
	v_pk_mul_f32 v[44:45], v[44:45], v[160:161]
	v_cvt_pk_bf16_f32 v206, v46, v47
	v_cvt_pk_bf16_f32 v207, v48, v49
	v_cvt_pk_bf16_f32 v208, v42, v43
	v_cvt_pk_bf16_f32 v209, v44, v45
	v_exp_f32_e32 v146, v146
	v_exp_f32_e32 v147, v147
	v_exp_f32_e32 v148, v148
	v_exp_f32_e32 v149, v149
	v_exp_f32_e32 v150, v150
	v_exp_f32_e32 v151, v151
	v_exp_f32_e32 v152, v152
	v_exp_f32_e32 v153, v153
	v_pk_mul_f32 v[30:31], v[30:31], v[22:23]
	v_pk_mul_f32 v[32:33], v[32:33], v[24:25]
	v_pk_mul_f32 v[26:27], v[26:27], v[18:19]
	v_pk_mul_f32 v[28:29], v[28:29], v[20:21]
	v_pk_fma_f32 v[146:147], v[146:147], v[252:253], v[252:253] op_sel:[0,1,1] op_sel_hi:[1,1,1]
	v_pk_fma_f32 v[148:149], v[148:149], v[252:253], v[252:253] op_sel:[0,1,1] op_sel_hi:[1,1,1]
	v_pk_fma_f32 v[150:151], v[150:151], v[252:253], v[252:253] op_sel:[0,1,1] op_sel_hi:[1,1,1]
	v_pk_fma_f32 v[152:153], v[152:153], v[252:253], v[252:253] op_sel:[0,1,1] op_sel_hi:[1,1,1]
	v_rcp_f32_e32 v146, v146
	v_rcp_f32_e32 v147, v147
	v_rcp_f32_e32 v148, v148
	v_rcp_f32_e32 v149, v149
	v_rcp_f32_e32 v150, v150
	v_rcp_f32_e32 v151, v151
	v_rcp_f32_e32 v152, v152
	v_rcp_f32_e32 v153, v153
	v_pk_mul_f32 v[154:155], v[14:15], v[214:215] op_sel_hi:[1,0]
	v_pk_mul_f32 v[156:157], v[16:17], v[214:215] op_sel_hi:[1,0]
	v_pk_mul_f32 v[158:159], v[10:11], v[214:215] op_sel_hi:[1,0]
	v_pk_mul_f32 v[160:161], v[12:13], v[214:215] op_sel_hi:[1,0]
	v_pk_mul_f32 v[30:31], v[30:31], v[146:147]
	v_pk_mul_f32 v[32:33], v[32:33], v[148:149]
	v_pk_mul_f32 v[26:27], v[26:27], v[150:151]
	v_pk_mul_f32 v[28:29], v[28:29], v[152:153]
	v_cvt_pk_bf16_f32 v210, v30, v31
	v_cvt_pk_bf16_f32 v211, v32, v33
	v_cvt_pk_bf16_f32 v212, v26, v27
	v_cvt_pk_bf16_f32 v213, v28, v29
	v_exp_f32_e32 v154, v154
	v_exp_f32_e32 v155, v155
	v_exp_f32_e32 v156, v156
	v_exp_f32_e32 v157, v157
	v_exp_f32_e32 v158, v158
	v_exp_f32_e32 v159, v159
	v_exp_f32_e32 v160, v160
	v_exp_f32_e32 v161, v161
	v_pk_mul_f32 v[14:15], v[14:15], v[6:7]
	v_pk_mul_f32 v[16:17], v[16:17], v[8:9]
	v_pk_mul_f32 v[10:11], v[10:11], v[2:3]
	v_pk_mul_f32 v[12:13], v[12:13], v[4:5]
	v_pk_fma_f32 v[154:155], v[154:155], v[214:215], v[214:215] op_sel:[0,1,1] op_sel_hi:[1,1,1]
	v_pk_fma_f32 v[156:157], v[156:157], v[214:215], v[214:215] op_sel:[0,1,1] op_sel_hi:[1,1,1]
	v_pk_fma_f32 v[158:159], v[158:159], v[214:215], v[214:215] op_sel:[0,1,1] op_sel_hi:[1,1,1]
	v_pk_fma_f32 v[160:161], v[160:161], v[214:215], v[214:215] op_sel:[0,1,1] op_sel_hi:[1,1,1]
	v_rcp_f32_e32 v154, v154
	v_rcp_f32_e32 v155, v155
	v_rcp_f32_e32 v156, v156
	v_rcp_f32_e32 v157, v157
	v_rcp_f32_e32 v158, v158
	v_rcp_f32_e32 v159, v159
	v_rcp_f32_e32 v160, v160
	v_rcp_f32_e32 v161, v161
	v_pk_mul_f32 v[14:15], v[14:15], v[154:155]
	v_pk_mul_f32 v[16:17], v[16:17], v[156:157]
	v_pk_mul_f32 v[10:11], v[10:11], v[158:159]
	v_pk_mul_f32 v[12:13], v[12:13], v[160:161]
	v_cvt_pk_bf16_f32 v74, v14, v15
	v_cvt_pk_bf16_f32 v75, v16, v17
	v_cvt_pk_bf16_f32 v76, v10, v11
	v_cvt_pk_bf16_f32 v77, v12, v13
	s_waitcnt vmcnt(0)
; __device__ __forceinline__ unsigned cvt_pk_bf16(float lo, float hi) { unsigned r; asm volatile("v_cvt_pk_bf16_f32 %0, %1, %2" : "=v"(r) : "v"(lo), "v"(hi)); return r; }
;     __device__ __forceinline__ void operator()(const f32x4 (&acc)[2][2][4][2], const Unit& u, int wr, int wc, int fr, int fq) const {
;     ...
;                 u32x4 w; w.x = cvt_pk_bf16(g0[0], g0[1]); w.y = cvt_pk_bf16(g0[2], g0[3]); w.z = cvt_pk_bf16(g1[0], g1[1]); w.w = cvt_pk_bf16(g1[2], g1[3]);
;                 *(u32x4*)(O + (size_t)row * ldc + col0 + (size_t)(row >> 12) * adj) = w; }
	global_store_dwordx4 v190, v[162:165], s[10:11]
	v_add_u32_e32 v190, s30, v190
	global_store_dwordx4 v190, v[166:169], s[10:11]
	v_add_u32_e32 v190, s30, v190
	global_store_dwordx4 v190, v[170:173], s[10:11]
	v_add_u32_e32 v190, s30, v190
	global_store_dwordx4 v190, v[174:177], s[10:11]
	v_add_u32_e32 v190, s31, v190
	global_store_dwordx4 v190, v[202:205], s[10:11]
	v_add_u32_e32 v190, s30, v190
	global_store_dwordx4 v190, v[206:209], s[10:11]
	v_add_u32_e32 v190, s30, v190
	global_store_dwordx4 v190, v[210:213], s[10:11]
	v_add_u32_e32 v190, s30, v190
	global_store_dwordx4 v190, v[74:77], s[10:11]
	s_andn2_b64 vcc, exec, s[8:9]
	s_mov_b64 s[4:5], -1
	s_branch .Lep_join
